# attention epilogue: gate loads requested at the start of the unit's final step (into dead mask-threshold registers), copied in the epilogue
# baseline (speedup 1.0000x reference)
.LBB0_825:
	s_or_b64 exec, exec, s[4:5]
	s_waitcnt lgkmcnt(0)
	v_lshlrev_b32_e32 v15, 9, v206
	v_lshlrev_b32_e32 v66, 1, v205
	ds_read2_b32 v[64:65], v207 offset0:32 offset1:33
	s_waitcnt lgkmcnt(0)
	v_mul_f32_e32 v32, v32, v64
	v_add3_u32 v15, s88, v15, v66
	ds_read2_b32 v[66:67], v207 offset0:34 offset1:35
	ds_read2_b32 v[68:69], v207 offset0:40 offset1:41
	ds_read2_b32 v[70:71], v207 offset0:42 offset1:43
	v_mul_f32_e32 v48, v48, v64
	v_mul_f32_e32 v33, v33, v65
	s_cmp_eq_u32 s1, 8
	v_cvt_pk_bf16_f32 v32, v48, v32
	ds_write_b16 v15, v32
	ds_write_b16_d16_hi v15, v32 offset:64
	v_mul_f32_e32 v32, v49, v65
	s_mov_b32 s0, s1
	v_cvt_pk_bf16_f32 v32, v32, v33
	ds_write_b16 v15, v32 offset:128
	ds_write_b16_d16_hi v15, v32 offset:192
	s_waitcnt lgkmcnt(6)
	v_mul_f32_e32 v32, v50, v66
	v_mul_f32_e32 v33, v34, v66
	s_nop 0
	v_cvt_pk_bf16_f32 v32, v32, v33
	ds_write_b16 v15, v32 offset:256
	ds_write_b16_d16_hi v15, v32 offset:320
	v_mul_f32_e32 v32, v51, v67
	v_mul_f32_e32 v33, v35, v67
	s_nop 0
	v_cvt_pk_bf16_f32 v32, v32, v33
	ds_write_b16 v15, v32 offset:384
	ds_write_b16_d16_hi v15, v32 offset:448
	s_waitcnt lgkmcnt(9)
	v_mul_f32_e32 v32, v52, v68
	v_mul_f32_e32 v33, v36, v68
	s_nop 0
	v_cvt_pk_bf16_f32 v32, v32, v33
	ds_write_b16 v15, v32 offset:1024
	ds_write_b16_d16_hi v15, v32 offset:1088
	v_mul_f32_e32 v32, v53, v69
	v_mul_f32_e32 v33, v37, v69
	s_nop 0
	v_cvt_pk_bf16_f32 v32, v32, v33
	ds_write_b16 v15, v32 offset:1152
	ds_write_b16_d16_hi v15, v32 offset:1216
	s_waitcnt lgkmcnt(12)
	v_mul_f32_e32 v32, v54, v70
	v_mul_f32_e32 v33, v38, v70
	s_nop 0
	v_cvt_pk_bf16_f32 v32, v32, v33
	ds_write_b16 v15, v32 offset:1280
	ds_write_b16_d16_hi v15, v32 offset:1344
	v_mul_f32_e32 v32, v55, v71
	v_mul_f32_e32 v33, v39, v71
	s_nop 0
	v_cvt_pk_bf16_f32 v34, v32, v33
	ds_read2_b32 v[32:33], v207 offset0:48 offset1:49
	ds_write_b16 v15, v34 offset:1408
	ds_write_b16_d16_hi v15, v34 offset:1472
	s_waitcnt lgkmcnt(2)
	v_mul_f32_e32 v48, v56, v32
	v_mul_f32_e32 v32, v40, v32
	ds_read2_b32 v[34:35], v207 offset0:50 offset1:51
	ds_read2_b32 v[36:37], v207 offset0:56 offset1:57
	ds_read2_b32 v[38:39], v207 offset0:58 offset1:59
	v_cvt_pk_bf16_f32 v32, v48, v32
	ds_write_b16 v15, v32 offset:2048
	ds_write_b16_d16_hi v15, v32 offset:2112
	v_mul_f32_e32 v32, v57, v33
	v_mul_f32_e32 v33, v41, v33
	s_nop 0
	v_cvt_pk_bf16_f32 v32, v32, v33
	ds_write_b16 v15, v32 offset:2176
	ds_write_b16_d16_hi v15, v32 offset:2240
	s_waitcnt lgkmcnt(6)
	v_mul_f32_e32 v32, v58, v34
	v_mul_f32_e32 v33, v42, v34
	v_add_u32_e32 v42, 8, v14
	v_cvt_pk_bf16_f32 v32, v32, v33
	ds_write_b16 v15, v32 offset:2304
	ds_write_b16_d16_hi v15, v32 offset:2368
	v_mul_f32_e32 v32, v59, v35
	v_mul_f32_e32 v33, v43, v35
	v_ashrrev_i32_e32 v43, 31, v42
	v_cvt_pk_bf16_f32 v32, v32, v33
	ds_write_b16 v15, v32 offset:2432
	ds_write_b16_d16_hi v15, v32 offset:2496
	s_waitcnt lgkmcnt(9)
	v_mul_f32_e32 v32, v60, v36
	v_mul_f32_e32 v33, v44, v36
	s_nop 0
	v_cvt_pk_bf16_f32 v32, v32, v33
	ds_write_b16 v15, v32 offset:3072
	ds_write_b16_d16_hi v15, v32 offset:3136
	v_mul_f32_e32 v32, v61, v37
	v_mul_f32_e32 v33, v45, v37
	s_nop 0
	v_cvt_pk_bf16_f32 v32, v32, v33
	ds_write_b16 v15, v32 offset:3200
	ds_write_b16_d16_hi v15, v32 offset:3264
	s_waitcnt lgkmcnt(12)
	v_mul_f32_e32 v32, v62, v38
	v_mul_f32_e32 v33, v46, v38
	s_cselect_b32 s101, 1, 0
	s_cmp_eq_u32 s100, 0
	s_cbranch_scc1 .Latt_gw0
	s_waitcnt vmcnt(6)
	s_branch .Latt_gw1

.Latt_gw1:
	s_cmp_lg_u32 s101, 0
	v_mov_b64_e32 v[96:97], v[220:221]
	v_mov_b64_e32 v[98:99], v[222:223]
	v_mov_b64_e32 v[10:11], v[224:225]
	v_mov_b64_e32 v[12:13], v[226:227]
	v_mov_b64_e32 v[6:7], v[228:229]
	v_mov_b64_e32 v[8:9], v[230:231]
	v_mov_b64_e32 v[2:3], v[232:233]
	v_mov_b64_e32 v[4:5], v[234:235]
	v_lshlrev_b32_e32 v46, 16, v96
	v_cvt_pk_bf16_f32 v32, v32, v33
	ds_write_b16 v15, v32 offset:3328
	ds_write_b16_d16_hi v15, v32 offset:3392
	v_mul_f32_e32 v32, v63, v39
	v_mul_f32_e32 v33, v47, v39
	v_and_b32_e32 v47, 0xffff0000, v96
	v_cvt_pk_bf16_f32 v32, v32, v33
	ds_write_b16 v15, v32 offset:3456
	ds_write_b16_d16_hi v15, v32 offset:3520
	v_add_u32_e32 v15, s88, v0
	s_waitcnt lgkmcnt(0)
	v_lshl_add_u32 v32, v14, 7, v15
	ds_read_b128 v[34:37], v32
	v_lshl_add_u64 v[32:33], s[46:47], 0, v[0:1]
	v_lshl_add_u32 v0, v42, 7, v15
	ds_read_b128 v[38:41], v0
	s_waitcnt lgkmcnt(1)
	v_lshlrev_b32_e32 v44, 16, v34
	v_and_b32_e32 v45, 0xffff0000, v34
	v_pk_mul_f32 v[44:45], v[46:47], v[44:45]
	v_lshlrev_b32_e32 v46, 16, v97
	v_cvt_pk_bf16_f32 v34, v44, v45
	v_lshlrev_b32_e32 v44, 16, v35
	v_and_b32_e32 v45, 0xffff0000, v35
	v_and_b32_e32 v47, 0xffff0000, v97
	v_pk_mul_f32 v[44:45], v[46:47], v[44:45]
	v_lshlrev_b32_e32 v46, 16, v98
	v_cvt_pk_bf16_f32 v35, v44, v45
	v_lshlrev_b32_e32 v44, 16, v36
	v_and_b32_e32 v45, 0xffff0000, v36
	v_and_b32_e32 v47, 0xffff0000, v98
	v_pk_mul_f32 v[44:45], v[46:47], v[44:45]
	v_lshlrev_b32_e32 v46, 16, v99
	v_cvt_pk_bf16_f32 v36, v44, v45
	v_lshlrev_b32_e32 v44, 16, v37
	v_and_b32_e32 v45, 0xffff0000, v37
	v_and_b32_e32 v47, 0xffff0000, v99
	v_pk_mul_f32 v[44:45], v[46:47], v[44:45]
	s_nop 0
	v_cvt_pk_bf16_f32 v37, v44, v45
	v_lshl_add_u64 v[44:45], v[32:33], 0, v[100:101]
	global_store_dwordx4 v[44:45], v[34:37], off
	s_nop 1
	v_lshl_add_u64 v[34:35], s[54:55], 0, v[42:43]
	s_waitcnt lgkmcnt(0)
	v_lshlrev_b32_e32 v36, 16, v38
	v_and_b32_e32 v37, 0xffff0000, v38
	s_nop 0
	v_lshlrev_b32_e32 v42, 16, v10
	v_and_b32_e32 v43, 0xffff0000, v10
	v_pk_mul_f32 v[36:37], v[42:43], v[36:37]
	v_lshlrev_b32_e32 v38, 16, v11
	v_cvt_pk_bf16_f32 v10, v36, v37
	v_lshlrev_b32_e32 v36, 16, v39
	v_and_b32_e32 v37, 0xffff0000, v39
	v_and_b32_e32 v39, 0xffff0000, v11
	v_pk_mul_f32 v[36:37], v[38:39], v[36:37]
	v_lshlrev_b32_e32 v38, 16, v12
	v_cvt_pk_bf16_f32 v11, v36, v37
	v_lshlrev_b32_e32 v36, 16, v40
	v_and_b32_e32 v37, 0xffff0000, v40
	v_and_b32_e32 v39, 0xffff0000, v12
	v_pk_mul_f32 v[36:37], v[38:39], v[36:37]
	v_lshlrev_b32_e32 v38, 16, v13
	v_cvt_pk_bf16_f32 v12, v36, v37
	v_lshlrev_b32_e32 v36, 16, v41
	v_and_b32_e32 v37, 0xffff0000, v41
	v_and_b32_e32 v39, 0xffff0000, v13
	v_pk_mul_f32 v[36:37], v[38:39], v[36:37]
	v_lshlrev_b64 v[34:35], 10, v[34:35]
	v_cvt_pk_bf16_f32 v13, v36, v37
	v_lshl_add_u64 v[34:35], v[32:33], 0, v[34:35]
	global_store_dwordx4 v[34:35], v[10:13], off
	v_add_u32_e32 v34, 16, v14
	v_lshl_add_u32 v0, v34, 7, v15
	ds_read_b128 v[10:13], v0
	s_nop 0
	v_lshlrev_b32_e32 v42, 16, v6
	v_and_b32_e32 v43, 0xffff0000, v6
	v_add_u32_e32 v14, 24, v14
	v_ashrrev_i32_e32 v35, 31, v34
	s_waitcnt lgkmcnt(0)
	v_lshlrev_b32_e32 v40, 16, v10
	v_and_b32_e32 v41, 0xffff0000, v10
	v_pk_mul_f32 v[40:41], v[42:43], v[40:41]
	v_lshlrev_b32_e32 v10, 16, v11
	v_cvt_pk_bf16_f32 v6, v40, v41
	v_and_b32_e32 v11, 0xffff0000, v11
	v_lshlrev_b32_e32 v40, 16, v7
	v_and_b32_e32 v41, 0xffff0000, v7
	v_pk_mul_f32 v[10:11], v[40:41], v[10:11]
	v_lshl_add_u32 v0, v14, 7, v15
	v_cvt_pk_bf16_f32 v7, v10, v11
	v_lshlrev_b32_e32 v10, 16, v12
	v_and_b32_e32 v11, 0xffff0000, v12
	v_lshlrev_b32_e32 v40, 16, v8
	v_and_b32_e32 v41, 0xffff0000, v8
	v_lshl_add_u64 v[38:39], s[54:55], 0, v[34:35]
	ds_read_b128 v[34:37], v0
	v_pk_mul_f32 v[10:11], v[40:41], v[10:11]
	v_lshlrev_b32_e32 v12, 16, v9
	v_cvt_pk_bf16_f32 v8, v10, v11
	v_lshlrev_b32_e32 v10, 16, v13
	v_and_b32_e32 v11, 0xffff0000, v13
	v_and_b32_e32 v13, 0xffff0000, v9
	v_pk_mul_f32 v[10:11], v[12:13], v[10:11]
	v_ashrrev_i32_e32 v15, 31, v14
	v_cvt_pk_bf16_f32 v9, v10, v11
	v_lshlrev_b64 v[10:11], 10, v[38:39]
	v_lshl_add_u64 v[10:11], v[32:33], 0, v[10:11]
	global_store_dwordx4 v[10:11], v[6:9], off
	s_nop 0
	v_lshlrev_b32_e32 v10, 16, v2
	v_and_b32_e32 v11, 0xffff0000, v2
	s_waitcnt lgkmcnt(0)
	v_lshlrev_b32_e32 v8, 16, v34
	v_and_b32_e32 v9, 0xffff0000, v34
	v_pk_mul_f32 v[8:9], v[10:11], v[8:9]
	v_lshlrev_b32_e32 v10, 16, v3
	v_cvt_pk_bf16_f32 v2, v8, v9
	v_lshlrev_b32_e32 v8, 16, v35
	v_and_b32_e32 v9, 0xffff0000, v35
	v_and_b32_e32 v11, 0xffff0000, v3
	v_pk_mul_f32 v[8:9], v[10:11], v[8:9]
	v_lshlrev_b32_e32 v10, 16, v4
	v_cvt_pk_bf16_f32 v3, v8, v9
	v_lshlrev_b32_e32 v8, 16, v36
	v_and_b32_e32 v9, 0xffff0000, v36
	v_and_b32_e32 v11, 0xffff0000, v4
	v_pk_mul_f32 v[8:9], v[10:11], v[8:9]
	v_lshl_add_u64 v[6:7], s[54:55], 0, v[14:15]
	v_cvt_pk_bf16_f32 v4, v8, v9
	v_lshlrev_b32_e32 v8, 16, v37
	v_and_b32_e32 v9, 0xffff0000, v37
	v_lshlrev_b32_e32 v10, 16, v5
	v_and_b32_e32 v11, 0xffff0000, v5
	v_pk_mul_f32 v[8:9], v[10:11], v[8:9]
	v_lshlrev_b64 v[6:7], 10, v[6:7]
	v_cvt_pk_bf16_f32 v5, v8, v9
	v_lshl_add_u64 v[6:7], v[32:33], 0, v[6:7]
	global_store_dwordx4 v[6:7], v[2:5], off
	s_waitcnt lgkmcnt(0)
	s_barrier
	s_cbranch_scc1 .LBB0_908

.LBB0_900:
	v_lshrrev_b32_e32 v236, 3, v204
	v_mov_b32_e32 v237, 0
	v_lshl_add_u64 v[236:237], s[54:55], 0, v[236:237]
	v_lshlrev_b64 v[236:237], 10, v[236:237]
	v_and_b32_e32 v238, 7, v204
	v_lshlrev_b32_e32 v238, 4, v238
	v_mov_b32_e32 v239, 0
	v_lshl_add_u64 v[238:239], s[44:45], 0, v[238:239]
	v_lshl_add_u64 v[236:237], v[236:237], 0, v[238:239]
	v_mov_b32_e32 v240, 0x2000
	v_mov_b32_e32 v241, 0
	v_lshl_add_u64 v[238:239], v[236:237], 0, v[240:241]
	global_load_dwordx4 v[220:223], v[236:237], off
	global_load_dwordx4 v[224:227], v[238:239], off
	v_lshl_add_u64 v[242:243], v[238:239], 0, v[240:241]
	v_lshl_add_u64 v[236:237], v[242:243], 0, v[240:241]
	global_load_dwordx4 v[228:231], v[242:243], off
	global_load_dwordx4 v[232:235], v[236:237], off
	ds_read_b128 v[2:5], v214 offset:40960
	v_add_u32_e32 v0, s22, v217
	s_waitcnt lgkmcnt(4)
	v_mfma_f32_32x32x16_bf16 v[112:127], v[196:199], v[176:179], v[64:79]
	v_add_f32_e32 v6, v96, v97
	v_add_f32_e32 v6, v98, v6
	v_add_f32_e32 v6, v99, v6
	v_add_f32_e32 v10, v100, v6
	v_cvt_pk_bf16_f32 v180, v96, v97
	ds_read_b128 v[6:9], v214 offset:41472
	s_waitcnt lgkmcnt(4)
	v_mfma_f32_32x32x16_bf16 v[64:79], v[184:187], v[176:179], v[64:79]
	v_add_f32_e32 v10, v101, v10
	v_add_f32_e32 v10, v102, v10
	v_add_f32_e32 v14, v103, v10
	v_cvt_pk_bf16_f32 v181, v98, v99
	ds_read_b128 v[10:13], v214 offset:43008
	s_waitcnt lgkmcnt(4)
	v_mfma_f32_32x32x16_bf16 v[112:127], v[188:191], v[168:171], v[112:127]
	v_add_f32_e32 v14, v104, v14
	v_add_f32_e32 v14, v105, v14
	v_add_f32_e32 v14, v106, v14
	v_cvt_pk_bf16_f32 v182, v100, v101
	ds_read_b128 v[96:99], v214 offset:43520
	s_waitcnt lgkmcnt(4)
	v_mfma_f32_32x32x16_bf16 v[64:79], v[192:195], v[168:171], v[64:79]
	v_add_f32_e32 v14, v107, v14
	v_add_f32_e32 v14, v108, v14
	v_add_f32_e32 v14, v109, v14
	v_cvt_pk_bf16_f32 v183, v102, v103
	ds_read_b128 v[100:103], v214 offset:45056
	s_waitcnt lgkmcnt(4)
	v_mfma_f32_32x32x16_bf16 v[112:127], v[2:5], v[164:167], v[112:127]
	v_add_f32_e32 v14, v110, v14
	v_add_f32_e32 v14, v111, v14
	v_add_f32_e32 v14, v80, v14
	v_cvt_pk_bf16_f32 v172, v104, v105
	ds_read_b128 v[2:5], v214 offset:45568
	s_waitcnt lgkmcnt(4)
	v_mfma_f32_32x32x16_bf16 v[64:79], v[6:9], v[164:167], v[64:79]
	v_add_f32_e32 v14, v81, v14
	v_add_f32_e32 v14, v82, v14
	v_add_f32_e32 v14, v83, v14
	v_cvt_pk_bf16_f32 v173, v106, v107
	ds_read_b128 v[104:107], v214 offset:47104
	s_waitcnt lgkmcnt(4)
	v_mfma_f32_32x32x16_bf16 v[112:127], v[10:13], v[156:159], v[112:127]
	v_add_f32_e32 v6, v84, v14
	v_add_f32_e32 v6, v85, v6
	v_cvt_pk_bf16_f32 v174, v108, v109
	v_cvt_pk_bf16_f32 v175, v110, v111
	ds_read_b128 v[108:111], v214 offset:47616
	s_waitcnt lgkmcnt(4)
	v_mfma_f32_32x32x16_bf16 v[64:79], v[96:99], v[156:159], v[64:79]
	v_add_f32_e32 v6, v86, v6
	v_add_f32_e32 v6, v87, v6
	v_cvt_pk_bf16_f32 v160, v80, v81
	v_cvt_pk_bf16_f32 v161, v82, v83
	ds_read_b64_tr_b16 v[128:129], v0 offset:49152
	ds_read_b64_tr_b16 v[130:131], v0 offset:49664
	s_waitcnt lgkmcnt(5)
	v_mfma_f32_32x32x16_bf16 v[112:127], v[100:103], v[148:151], v[112:127]
	v_add_f32_e32 v6, v88, v6
	v_add_f32_e32 v6, v89, v6
	v_cvt_pk_bf16_f32 v162, v84, v85
	v_cvt_pk_bf16_f32 v163, v86, v87
	ds_read_b64_tr_b16 v[10:11], v0 offset:53248
	ds_read_b64_tr_b16 v[12:13], v0 offset:53760
	s_waitcnt lgkmcnt(6)
	v_mfma_f32_32x32x16_bf16 v[64:79], v[2:5], v[148:151], v[64:79]
	v_add_f32_e32 v6, v90, v6
	v_add_f32_e32 v14, v91, v6
	v_cvt_pk_bf16_f32 v152, v88, v89
	v_cvt_pk_bf16_f32 v153, v90, v91
	ds_read_b64_tr_b16 v[6:7], v0 offset:50176
	ds_read_b64_tr_b16 v[8:9], v0 offset:50688
	s_waitcnt lgkmcnt(7)
	v_mfma_f32_32x32x16_bf16 v[112:127], v[104:107], v[144:147], v[112:127]
	v_add_f32_e32 v2, v92, v14
	v_add_f32_e32 v14, v93, v2
	v_cvt_pk_bf16_f32 v154, v92, v93
	ds_read_b64_tr_b16 v[2:3], v0 offset:54272
	ds_read_b64_tr_b16 v[4:5], v0 offset:54784
	s_waitcnt lgkmcnt(8)
	v_mfma_f32_32x32x16_bf16 v[64:79], v[108:111], v[144:147], v[64:79]
	v_add_f32_e32 v14, v94, v14
	v_add_f32_e32 v14, v95, v14
	v_cvt_pk_bf16_f32 v155, v94, v95
	s_cmp_eq_u32 s100, 0
	s_cbranch_scc1 .Latt_q_nopf
	v_lshrrev_b32_e32 v252, 5, v204
	v_lshlrev_b32_e32 v252, 4, v252
	v_and_b32_e32 v254, 31, v204
	v_mul_u32_u24_e32 v254, 0x600, v254
	v_add_u32_e32 v252, v252, v254
	v_mov_b32_e32 v253, 0
	v_lshl_add_u64 v[252:253], s[98:99], 0, v[252:253]
	global_load_dwordx4 v[176:179], v[252:253], off
	global_load_dwordx4 v[168:171], v[252:253], off offset:32
	global_load_dwordx4 v[164:167], v[252:253], off offset:64
	global_load_dwordx4 v[156:159], v[252:253], off offset:96
	global_load_dwordx4 v[148:151], v[252:253], off offset:128
	global_load_dwordx4 v[144:147], v[252:253], off offset:160

.LBB0_903:
	v_ashrrev_i32_e32 v14, 3, v204
	v_ashrrev_i32_e32 v15, 31, v14
	v_and_b32_e32 v0, 56, v211
	v_lshl_add_u64 v[2:3], s[54:55], 0, v[14:15]
	v_lshlrev_b32_e32 v0, 1, v0
	v_lshl_add_u64 v[4:5], s[44:45], 0, v[0:1]
	v_lshlrev_b64 v[100:101], 10, v[2:3]
	v_lshl_add_u64 v[2:3], v[4:5], 0, v[100:101]
	v_add_co_u32_e32 v4, vcc, 0x2000, v2
	v_add_f32_e32 v15, v80, v81
	s_nop 0
	v_addc_co_u32_e32 v5, vcc, 0, v3, vcc
	v_add_co_u32_e32 v4, vcc, 0x4000, v2
	v_add_f32_e32 v15, v82, v15
	s_nop 0
	v_addc_co_u32_e32 v5, vcc, 0, v3, vcc
	v_add_co_u32_e32 v2, vcc, 0x6000, v2
	v_add_f32_e32 v15, v83, v15
	s_nop 0
	v_addc_co_u32_e32 v3, vcc, 0, v3, vcc
	s_nop 0
	v_add_f32_e32 v15, v84, v15
	v_add_f32_e32 v15, v85, v15
	v_add_f32_e32 v15, v86, v15
	v_add_f32_e32 v15, v87, v15
	v_add_f32_e32 v15, v88, v15
	v_add_f32_e32 v15, v89, v15
	v_add_f32_e32 v15, v90, v15
	v_add_f32_e32 v15, v91, v15
	v_add_f32_e32 v15, v92, v15
	v_add_f32_e32 v15, v93, v15
	v_add_f32_e32 v15, v94, v15
	v_add_f32_e32 v15, v95, v15
	v_add_f32_e32 v15, v15, v64
	v_add_f32_e32 v15, v65, v15
	v_add_f32_e32 v15, v66, v15
	v_add_f32_e32 v15, v67, v15
	v_add_f32_e32 v15, v68, v15
	v_add_f32_e32 v15, v69, v15
	v_add_f32_e32 v15, v70, v15
	v_add_f32_e32 v15, v71, v15
	v_add_f32_e32 v15, v72, v15
	v_add_f32_e32 v15, v73, v15
	v_add_f32_e32 v15, v74, v15
	v_add_f32_e32 v15, v75, v15
	v_add_f32_e32 v15, v76, v15
	v_add_f32_e32 v15, v77, v15
	v_add_f32_e32 v15, v78, v15
	v_add_f32_e32 v15, v79, v15
	s_add_i32 s0, 0, 0xc000
	v_add_f32_e32 v15, v112, v15
	v_cvt_pk_bf16_f32 v64, v64, v65
	v_add3_u32 v102, v209, s0, v210
	v_cvt_pk_bf16_f32 v80, v80, v81
	v_cvt_pk_bf16_f32 v81, v82, v83
	v_cvt_pk_bf16_f32 v82, v84, v85
	v_cvt_pk_bf16_f32 v83, v86, v87
	v_cvt_pk_bf16_f32 v84, v88, v89
	v_cvt_pk_bf16_f32 v85, v90, v91
	v_cvt_pk_bf16_f32 v86, v92, v93
	v_cvt_pk_bf16_f32 v87, v94, v95
	v_cvt_pk_bf16_f32 v65, v66, v67
	v_cvt_pk_bf16_f32 v66, v68, v69
	v_cvt_pk_bf16_f32 v67, v70, v71
	v_cvt_pk_bf16_f32 v68, v72, v73
	v_cvt_pk_bf16_f32 v69, v74, v75
	v_cvt_pk_bf16_f32 v70, v76, v77
	v_cvt_pk_bf16_f32 v71, v78, v79
	v_add3_u32 v106, v102, v208, s12
	ds_read_b64_tr_b16 v[72:73],v106 offset:0
	ds_read_b64_tr_b16 v[74:75],v106 offset:512
	ds_read_b64_tr_b16 v[76:77],v106 offset:1024
	ds_read_b64_tr_b16 v[78:79],v106 offset:1536
	ds_read_b64_tr_b16 v[88:89],v106 offset:2048
	ds_read_b64_tr_b16 v[90:91],v106 offset:2560
	ds_read_b64_tr_b16 v[92:93],v106 offset:3072
	ds_read_b64_tr_b16 v[94:95],v106 offset:3584
	s_waitcnt lgkmcnt(0)
	s_nop 0
	v_mfma_f32_32x32x16_bf16 v[48:63], v[80:83], v[72:75], v[48:63]
	ds_read_b64_tr_b16 v[72:73],v106 offset:4096
	ds_read_b64_tr_b16 v[74:75],v106 offset:4608
	v_mfma_f32_32x32x16_bf16 v[48:63], v[84:87], v[76:79], v[48:63]
	ds_read_b64_tr_b16 v[76:77],v106 offset:5120
	ds_read_b64_tr_b16 v[78:79],v106 offset:5632
	v_mfma_f32_32x32x16_bf16 v[48:63], v[64:67], v[88:91], v[48:63]
	ds_read_b64_tr_b16 v[88:89],v106 offset:6144
	ds_read_b64_tr_b16 v[90:91],v106 offset:6656
	ds_read_b64_tr_b16 v[102:103],v106 offset:7168
	ds_read_b64_tr_b16 v[104:105],v106 offset:7680
	s_waitcnt lgkmcnt(0)
	v_mfma_f32_32x32x16_bf16 v[48:63], v[68:71], v[92:95], v[48:63]
	v_mfma_f32_32x32x16_bf16 v[32:47], v[80:83], v[72:75], v[32:47]
	v_cmp_gt_u32_e32 vcc, 32, v204
	v_mfma_f32_32x32x16_bf16 v[32:47], v[84:87], v[76:79], v[32:47]
	v_mfma_f32_32x32x16_bf16 v[32:47], v[64:67], v[88:91], v[32:47]
	v_mov_b32_e32 v64, v15
	s_nop 1
	v_permlane32_swap_b32_e32 v15, v64
	v_mfma_f32_32x32x16_bf16 v[32:47], v[68:71], v[102:105], v[32:47]
	s_and_saveexec_b64 s[4:5], vcc
	s_cbranch_execz .LBB0_825
	v_add_f32_e32 v15, v15, v64
	v_rcp_f32_e32 v15, v15
	v_lshl_add_u32 v64, v204, 2, s87
	ds_write_b32 v64, v15 offset:128
	s_branch .LBB0_825
